# grid barriers 1..10: monotonic arrival counter in d_ws (one write-back, one non-returning atomic, poll, one invalidate per workgroup) instead of cooperative-groups grid.sync; counter zeroed at entry a
# speedup vs baseline: 1.0202x; 1.0162x over previous
; #define LAS __attribute__((address_space(3)))
; __global__ void __launch_bounds__(512) fwd_mega(Args a) {
;     extern __shared__ __attribute__((aligned(16))) unsigned char lds_raw[];
;     LAS unsigned char* lds = (LAS unsigned char*)lds_raw;
;     cg::grid_group grid = cg::this_grid();
;     const int tid = threadIdx.x, lane = tid & 63, wave = __builtin_amdgcn_readfirstlane(tid >> 6);
;     const int G = gridDim.x, bx = blockIdx.x;
;     const int vcu = (G % 8 == 0) ? (bx % 8) * (G / 8) + bx / 8 : bx;
;     unsigned char* ws = a.ws;
_Z8fwd_mega4Args:
	s_load_dwordx16 s[72:87], s[0:1], 0x0
	s_load_dwordx8 s[24:31], s[0:1], 0x80
	s_load_dwordx4 s[52:55], s[0:1], 0xa0
	s_load_dword s3, s[0:1], 0xb0
	s_add_u32 s58, s0, 0xb0
	s_mov_b32 s60, s2
	s_addc_u32 s59, s1, 0
	v_and_b32_e32 v162, 0x3ff, v0
	s_waitcnt lgkmcnt(0)
	s_cmp_eq_u32 s60, 0
	s_cbranch_scc0 .Lsm_init_done
	v_mov_b32_e32 v254, 0x400
	v_mov_b32_e32 v255, 0
	global_store_dword v254, v255, s[52:53]
.Lsm_init_done:
	s_and_b32 s2, s3, 7
	v_readfirstlane_b32 s61, v162
	s_cmp_lg_u32 s2, 0
	s_mov_b32 s2, s60
	s_cbranch_scc1 .LBB0_2
	s_ashr_i32 s4, s60, 31
	s_lshr_b32 s4, s4, 29
	s_add_i32 s4, s60, s4
	s_and_b32 s5, s4, -8
	s_ashr_i32 s2, s3, 3
	s_sub_i32 s5, s60, s5
	s_mul_i32 s2, s2, s5
	s_ashr_i32 s4, s4, 3
	s_add_i32 s2, s2, s4

; __global__ void __launch_bounds__(512) fwd_mega(Args a) {
;     ...
;     SEAM(1);
.LBB0_170:
	s_cmp_gt_i32 s55, 2
	s_cselect_b64 s[0:1], -1, 0
	s_and_b64 s[4:5], s[20:21], s[0:1]
	s_andn2_b64 vcc, exec, s[4:5]
	s_cbranch_vccnz .LBB0_186
	v_readlane_b32 s8, v253, 42
	v_readlane_b32 s9, v253, 43
	s_waitcnt vmcnt(0) lgkmcnt(0)
	s_barrier
	v_readfirstlane_b32 s98, v162
	s_nop 3
	s_cmp_lt_u32 s98, 64
	s_cbranch_scc0 .Lsm1_wait
	buffer_wbl2 sc1
	s_waitcnt vmcnt(0)
	s_mov_b64 vcc, exec
	s_mov_b64 exec, 1
	v_mov_b32_e32 v254, 0x400
	v_mov_b32_e32 v255, 1
	global_atomic_add v254, v255, s[52:53]
	s_lshr_b32 s99, s56, 3
	s_mul_i32 s99, s99, 1
	s_mov_b32 s100, 0
.Lsm1_poll:
	global_load_dword v255, v254, s[52:53] sc1
	s_waitcnt vmcnt(0)
	v_readfirstlane_b32 s98, v255
	s_nop 3
	s_cmp_ge_u32 s98, s99
	s_cbranch_scc1 .Lsm1_done
	s_add_u32 s100, s100, 1
	s_cmp_lt_u32 s100, 0x4000
	s_cbranch_scc0 .Lsm1_done
	s_sleep 1
	s_branch .Lsm1_poll
.Lsm1_done:
	s_mov_b64 exec, vcc
	buffer_inv sc1
	s_waitcnt vmcnt(0)

; __global__ void __launch_bounds__(512) fwd_mega(Args a) {
;     ...
;     SEAM(2);
.LBB0_285:
	s_cmp_gt_i32 s55, 3
	s_cselect_b64 s[0:1], -1, 0
	s_and_b64 s[4:5], s[12:13], s[0:1]
	v_readlane_b32 s92, v253, 42
	s_andn2_b64 vcc, exec, s[4:5]
	v_readlane_b32 s93, v253, 43
	s_cbranch_vccnz .LBB0_301
	v_readlane_b32 s6, v253, 48
	s_waitcnt vmcnt(0) lgkmcnt(0)
	s_barrier
	v_readfirstlane_b32 s98, v162
	s_nop 3
	s_cmp_lt_u32 s98, 64
	s_cbranch_scc0 .Lsm2_wait
	buffer_wbl2 sc1
	s_waitcnt vmcnt(0)
	s_mov_b64 vcc, exec
	s_mov_b64 exec, 1
	v_mov_b32_e32 v254, 0x400
	v_mov_b32_e32 v255, 1
	global_atomic_add v254, v255, s[52:53]
	s_lshr_b32 s99, s56, 3
	s_mul_i32 s99, s99, 2
	s_mov_b32 s100, 0

; __global__ void __launch_bounds__(512) fwd_mega(Args a) {
;     ...
;     SEAM(3);
.LBB0_682:
	s_cmp_gt_i32 s55, 4
	s_cselect_b64 s[0:1], -1, 0
	s_and_b64 s[4:5], s[44:45], s[0:1]
	v_readlane_b32 s76, v253, 26
	s_andn2_b64 vcc, exec, s[4:5]
	v_readlane_b32 s77, v253, 27
	v_readlane_b32 s80, v253, 30
	v_readlane_b32 s81, v253, 31
	v_readlane_b32 s82, v253, 32
	v_readlane_b32 s83, v253, 33
	v_readlane_b32 s84, v253, 34
	v_readlane_b32 s85, v253, 35
	v_readlane_b32 s94, v253, 48
	v_readlane_b32 s78, v253, 28
	v_readlane_b32 s79, v253, 29
	v_readlane_b32 s86, v253, 36
	v_readlane_b32 s87, v253, 37
	v_readlane_b32 s88, v253, 38
	v_readlane_b32 s89, v253, 39
	v_readlane_b32 s90, v253, 40
	v_readlane_b32 s91, v253, 41
	s_cbranch_vccnz .LBB0_698
	s_waitcnt vmcnt(0) lgkmcnt(0)
	s_barrier
	v_readfirstlane_b32 s98, v162
	s_nop 3
	s_cmp_lt_u32 s98, 64
	s_cbranch_scc0 .Lsm3_wait
	buffer_wbl2 sc1
	s_waitcnt vmcnt(0)
	s_mov_b64 vcc, exec
	s_mov_b64 exec, 1
	v_mov_b32_e32 v254, 0x400
	v_mov_b32_e32 v255, 1
	global_atomic_add v254, v255, s[52:53]
	s_lshr_b32 s99, s56, 3
	s_mul_i32 s99, s99, 3
	s_mov_b32 s100, 0

; __global__ void __launch_bounds__(512) fwd_mega(Args a) {
;     ...
;     SEAM(4);
.LBB0_723:
	s_cmp_gt_i32 s55, 5
	s_cselect_b64 s[0:1], -1, 0
	s_and_b64 s[4:5], s[4:5], s[0:1]
	s_andn2_b64 vcc, exec, s[4:5]
	s_cbranch_vccnz .LBB0_739
	s_waitcnt vmcnt(0) lgkmcnt(0)
	s_barrier
	v_readfirstlane_b32 s98, v162
	s_nop 3
	s_cmp_lt_u32 s98, 64
	s_cbranch_scc0 .Lsm4_wait
	buffer_wbl2 sc1
	s_waitcnt vmcnt(0)
	s_mov_b64 vcc, exec
	s_mov_b64 exec, 1
	v_mov_b32_e32 v254, 0x400
	v_mov_b32_e32 v255, 1
	global_atomic_add v254, v255, s[52:53]
	s_lshr_b32 s99, s56, 3
	s_mul_i32 s99, s99, 4
	s_mov_b32 s100, 0

; __global__ void __launch_bounds__(512) fwd_mega(Args a) {
;     ...
;     SEAM(5);
.LBB0_788:
	s_cmp_gt_i32 s55, 6
	s_cselect_b64 s[0:1], -1, 0
	s_and_b64 s[4:5], s[4:5], s[0:1]
	s_andn2_b64 vcc, exec, s[4:5]
	s_cbranch_vccnz .LBB0_804
	s_waitcnt vmcnt(0) lgkmcnt(0)
	s_barrier
	v_readfirstlane_b32 s98, v162
	s_nop 3
	s_cmp_lt_u32 s98, 64
	s_cbranch_scc0 .Lsm5_wait
	buffer_wbl2 sc1
	s_waitcnt vmcnt(0)
	s_mov_b64 vcc, exec
	s_mov_b64 exec, 1
	v_mov_b32_e32 v254, 0x400
	v_mov_b32_e32 v255, 1
	global_atomic_add v254, v255, s[52:53]
	s_lshr_b32 s99, s56, 3
	s_mul_i32 s99, s99, 5
	s_mov_b32 s100, 0

; __global__ void __launch_bounds__(512) fwd_mega(Args a) {
;     ...
;     SEAM(6);
.LBB0_863:
	s_cmp_gt_i32 s55, 7
	s_cselect_b64 s[0:1], -1, 0
	s_and_b64 s[4:5], s[18:19], s[0:1]
	s_andn2_b64 vcc, exec, s[4:5]
	s_cbranch_vccnz .LBB0_879
	s_waitcnt vmcnt(0) lgkmcnt(0)
	s_barrier
	v_readfirstlane_b32 s98, v162
	s_nop 3
	s_cmp_lt_u32 s98, 64
	s_cbranch_scc0 .Lsm6_wait
	buffer_wbl2 sc1
	s_waitcnt vmcnt(0)
	s_mov_b64 vcc, exec
	s_mov_b64 exec, 1
	v_mov_b32_e32 v254, 0x400
	v_mov_b32_e32 v255, 1
	global_atomic_add v254, v255, s[52:53]
	s_lshr_b32 s99, s56, 3
	s_mul_i32 s99, s99, 6
	s_mov_b32 s100, 0

; __global__ void __launch_bounds__(512) fwd_mega(Args a) {
;     ...
;     SEAM(7);
.LBB0_882:
	s_cmp_gt_i32 s55, 8
	s_cselect_b64 s[0:1], -1, 0
	s_and_b64 s[4:5], s[4:5], s[0:1]
	v_readlane_b32 s68, v253, 24
	s_andn2_b64 vcc, exec, s[4:5]
	v_readlane_b32 s69, v253, 25
	s_cbranch_vccnz .LBB0_898
	s_waitcnt vmcnt(0) lgkmcnt(0)
	s_barrier
	v_readfirstlane_b32 s98, v162
	s_nop 3
	s_cmp_lt_u32 s98, 64
	s_cbranch_scc0 .Lsm7_wait
	buffer_wbl2 sc1
	s_waitcnt vmcnt(0)
	s_mov_b64 vcc, exec
	s_mov_b64 exec, 1
	v_mov_b32_e32 v254, 0x400
	v_mov_b32_e32 v255, 1
	global_atomic_add v254, v255, s[52:53]
	s_lshr_b32 s99, s56, 3
	s_mul_i32 s99, s99, 7
	s_mov_b32 s100, 0

; __global__ void __launch_bounds__(512) fwd_mega(Args a) {
;     ...
;     SEAM(8);
.LBB0_927:
	s_cmp_gt_i32 s55, 9
	s_cselect_b64 s[0:1], -1, 0
	s_and_b64 s[4:5], s[22:23], s[0:1]
	s_andn2_b64 vcc, exec, s[4:5]
	s_cbranch_vccnz .LBB0_943
	s_waitcnt vmcnt(0) lgkmcnt(0)
	s_barrier
	v_readfirstlane_b32 s98, v162
	s_nop 3
	s_cmp_lt_u32 s98, 64
	s_cbranch_scc0 .Lsm8_wait
	buffer_wbl2 sc1
	s_waitcnt vmcnt(0)
	s_mov_b64 vcc, exec
	s_mov_b64 exec, 1
	v_mov_b32_e32 v254, 0x400
	v_mov_b32_e32 v255, 1
	global_atomic_add v254, v255, s[52:53]
	s_lshr_b32 s99, s56, 3
	s_mul_i32 s99, s99, 8
	s_mov_b32 s100, 0

; __global__ void __launch_bounds__(512) fwd_mega(Args a) {
;     ...
;     SEAM(9);
.LBB0_954:
	s_cmp_gt_i32 s55, 10
	s_cselect_b64 s[0:1], -1, 0
	s_and_b64 s[4:5], s[4:5], s[0:1]
	s_andn2_b64 vcc, exec, s[4:5]
	s_cbranch_vccnz .LBB0_970
	s_waitcnt vmcnt(0) lgkmcnt(0)
	s_barrier
	v_readfirstlane_b32 s98, v162
	s_nop 3
	s_cmp_lt_u32 s98, 64
	s_cbranch_scc0 .Lsm9_wait
	buffer_wbl2 sc1
	s_waitcnt vmcnt(0)
	s_mov_b64 vcc, exec
	s_mov_b64 exec, 1
	v_mov_b32_e32 v254, 0x400
	v_mov_b32_e32 v255, 1
	global_atomic_add v254, v255, s[52:53]
	s_lshr_b32 s99, s56, 3
	s_mul_i32 s99, s99, 9
	s_mov_b32 s100, 0

; __global__ void __launch_bounds__(512) fwd_mega(Args a) {
;     ...
;     SEAM(10);
.LBB0_1033:
	s_cmp_gt_i32 s55, 11
	s_cselect_b64 s[0:1], -1, 0
	s_and_b64 s[2:3], s[8:9], s[0:1]
	s_andn2_b64 vcc, exec, s[2:3]
	s_cbranch_vccnz .LBB0_1049
	s_waitcnt vmcnt(0) lgkmcnt(0)
	s_barrier
	v_readfirstlane_b32 s98, v162
	s_nop 3
	s_cmp_lt_u32 s98, 64
	s_cbranch_scc0 .Lsm10_wait
	buffer_wbl2 sc1
	s_waitcnt vmcnt(0)
	s_mov_b64 vcc, exec
	s_mov_b64 exec, 1
	v_mov_b32_e32 v254, 0x400
	v_mov_b32_e32 v255, 1
	global_atomic_add v254, v255, s[52:53]
	s_lshr_b32 s99, s56, 3
	s_mul_i32 s99, s99, 10
	s_mov_b32 s100, 0
